# GEMM: first K-loop iteration peeled with C=0 first-touch MFMAs; per-tile accumulator zeroing (128 v_mov/wave) eliminated
# speedup vs baseline: 1.0082x; 1.0041x over previous
.LBB0_246:
	s_andn2_b64 vcc, exec, s[18:19]
	s_cbranch_vccnz .Lk_zero_skip
	s_add_u32 s44, s44, 0x80
	s_addc_u32 s45, s45, 0
	s_add_u32 s23, s46, 0x100
	s_addc_u32 s48, s47, 0
	s_mov_b32 s46, 0
	s_add_i32 s49, s46, 2
	s_add_u32 s69, s44, 0x80
	s_addc_u32 s47, s45, 0
	s_add_i32 s80, 0, 0x10000
	s_cmp_eq_u32 s90, s46
	s_cselect_b32 s47, s65, s47
	s_cselect_b32 s46, s64, s69
	s_cselect_b32 s71, s67, s48
	s_cselect_b32 s70, s66, s23
	s_add_i32 s69, 0, 0x14000
	v_add_u32_e32 v140, s80, v227
	v_add_u32_e32 v152, s69, v227
	ds_read_b128 v[128:131], v140
	ds_read_b128 v[132:135], v140 offset:1024
	ds_read_b128 v[136:139], v140 offset:2048
	ds_read_b128 v[140:143], v140 offset:3072
	ds_read_b128 v[144:147], v152
	ds_read_b128 v[148:151], v152 offset:1024
	ds_read_b128 v[174:177], v152 offset:2048
	ds_read_b128 v[178:181], v152 offset:3072
	v_lshl_add_u64 v[210:211], s[44:45], 0, v[170:171]
	s_add_i32 m0, s50, 0xc000
	ds_read_b128 v[182:185], v230
	ds_read_b128 v[186:189], v230 offset:1024
	ds_read_b128 v[190:193], v230 offset:2048
	ds_read_b128 v[194:197], v230 offset:3072
	ds_read_b128 v[198:201], v230 offset:4096
	ds_read_b128 v[202:205], v230 offset:5120
	ds_read_b128 v[206:209], v230 offset:6144
	ds_read_b128 v[232:235], v230 offset:7168
	global_load_lds_dwordx4 v[210:211], off
	v_lshl_add_u64 v[210:211], s[44:45], 0, v[172:173]
	s_add_i32 m0, s50, 0xe000
	s_nop 0
	global_load_lds_dwordx4 v[210:211], off
	s_waitcnt vmcnt(8)
	s_waitcnt lgkmcnt(0)
	s_barrier
	s_setprio 1
	s_waitcnt lgkmcnt(0)
	v_mfma_f32_16x16x32_bf16 v[16:19], v[128:131], v[182:185], 0
	v_mfma_f32_16x16x32_bf16 v[28:31], v[136:139], v[182:185], 0
	v_mfma_f32_16x16x32_bf16 v[12:15], v[128:131], v[190:193], 0
	v_mfma_f32_16x16x32_bf16 v[8:11], v[136:139], v[190:193], 0
	v_mfma_f32_16x16x32_bf16 v[124:127], v[128:131], v[198:201], 0
	v_mfma_f32_16x16x32_bf16 v[120:123], v[136:139], v[198:201], 0
	v_mfma_f32_16x16x32_bf16 v[108:111], v[128:131], v[206:209], 0
	v_mfma_f32_16x16x32_bf16 v[104:107], v[136:139], v[206:209], 0
	v_mfma_f32_16x16x32_bf16 v[16:19], v[132:135], v[186:189], v[16:19]
	v_mfma_f32_16x16x32_bf16 v[28:31], v[140:143], v[186:189], v[28:31]
	v_mfma_f32_16x16x32_bf16 v[12:15], v[132:135], v[194:197], v[12:15]
	v_mfma_f32_16x16x32_bf16 v[8:11], v[140:143], v[194:197], v[8:11]
	v_mfma_f32_16x16x32_bf16 v[124:127], v[132:135], v[202:205], v[124:127]
	v_mfma_f32_16x16x32_bf16 v[120:123], v[140:143], v[202:205], v[120:123]
	v_mfma_f32_16x16x32_bf16 v[108:111], v[132:135], v[232:235], v[108:111]
	v_mfma_f32_16x16x32_bf16 v[104:107], v[140:143], v[232:235], v[104:107]
	s_setprio 0
	s_setprio 1
	v_mfma_f32_16x16x32_bf16 v[24:27], v[144:147], v[182:185], 0
	v_mfma_f32_16x16x32_bf16 v[20:23], v[174:177], v[182:185], 0
	v_mfma_f32_16x16x32_bf16 v[4:7], v[144:147], v[190:193], 0
	v_mfma_f32_16x16x32_bf16 v[0:3], v[174:177], v[190:193], 0
	v_mfma_f32_16x16x32_bf16 v[116:119], v[144:147], v[198:201], 0
	v_mfma_f32_16x16x32_bf16 v[112:115], v[174:177], v[198:201], 0
	v_mfma_f32_16x16x32_bf16 v[100:103], v[144:147], v[206:209], 0
	v_mfma_f32_16x16x32_bf16 v[96:99], v[174:177], v[206:209], 0
	v_mfma_f32_16x16x32_bf16 v[24:27], v[148:151], v[186:189], v[24:27]
	v_mfma_f32_16x16x32_bf16 v[20:23], v[178:181], v[186:189], v[20:23]
	v_mfma_f32_16x16x32_bf16 v[4:7], v[148:151], v[194:197], v[4:7]
	v_mfma_f32_16x16x32_bf16 v[0:3], v[178:181], v[194:197], v[0:3]
	v_mfma_f32_16x16x32_bf16 v[116:119], v[148:151], v[202:205], v[116:119]
	v_mfma_f32_16x16x32_bf16 v[112:115], v[178:181], v[202:205], v[112:115]
	v_mfma_f32_16x16x32_bf16 v[100:103], v[148:151], v[232:235], v[100:103]
	v_mfma_f32_16x16x32_bf16 v[96:99], v[178:181], v[232:235], v[96:99]
	s_setprio 0
	s_barrier
	s_add_i32 s80, s80, s3
	v_lshl_add_u64 v[210:211], s[70:71], 0, v[160:161]
	s_mov_b32 m0, s80
	ds_read_b128 v[182:185], v230 offset:16384
	ds_read_b128 v[186:189], v230 offset:17408
	ds_read_b128 v[190:193], v230 offset:18432
	ds_read_b128 v[194:197], v230 offset:19456
	ds_read_b128 v[198:201], v230 offset:20480
	ds_read_b128 v[202:205], v230 offset:21504
	ds_read_b128 v[206:209], v230 offset:22528
	ds_read_b128 v[232:235], v230 offset:23552
	global_load_lds_dwordx4 v[210:211], off
	s_add_i32 m0, s80, 0x2000
	v_lshl_add_u64 v[236:237], s[70:71], 0, v[164:165]
	s_add_u32 s70, s70, s26
	s_addc_u32 s71, s71, 0
	s_add_i32 s69, s69, s3
	global_load_lds_dwordx4 v[236:237], off
	v_lshl_add_u64 v[238:239], s[70:71], 0, v[160:161]
	s_mov_b32 m0, s69
	v_lshl_add_u64 v[240:241], s[70:71], 0, v[164:165]
	global_load_lds_dwordx4 v[238:239], off
	s_add_i32 m0, s69, 0x2000
	v_lshl_add_u64 v[242:243], s[46:47], 0, v[158:159]
	global_load_lds_dwordx4 v[240:241], off
	s_mov_b32 m0, s50
	v_lshl_add_u64 v[244:245], s[46:47], 0, v[162:163]
	global_load_lds_dwordx4 v[242:243], off
	s_mov_b32 m0, s51
	s_nop 0
	global_load_lds_dwordx4 v[244:245], off
	s_waitcnt vmcnt(8)
	s_waitcnt lgkmcnt(0)
	s_barrier
	s_setprio 1
	s_waitcnt lgkmcnt(0)
	v_mfma_f32_16x16x32_bf16 v[92:95], v[128:131], v[182:185], 0
	v_mfma_f32_16x16x32_bf16 v[88:91], v[136:139], v[182:185], 0
	v_mfma_f32_16x16x32_bf16 v[76:79], v[128:131], v[190:193], 0
	v_mfma_f32_16x16x32_bf16 v[72:75], v[136:139], v[190:193], 0
	v_mfma_f32_16x16x32_bf16 v[60:63], v[128:131], v[198:201], 0
	v_mfma_f32_16x16x32_bf16 v[56:59], v[136:139], v[198:201], 0
	v_mfma_f32_16x16x32_bf16 v[44:47], v[128:131], v[206:209], 0
	v_mfma_f32_16x16x32_bf16 v[40:43], v[136:139], v[206:209], 0
	v_mfma_f32_16x16x32_bf16 v[92:95], v[132:135], v[186:189], v[92:95]
	v_mfma_f32_16x16x32_bf16 v[88:91], v[140:143], v[186:189], v[88:91]
	v_mfma_f32_16x16x32_bf16 v[76:79], v[132:135], v[194:197], v[76:79]
	v_mfma_f32_16x16x32_bf16 v[72:75], v[140:143], v[194:197], v[72:75]
	v_mfma_f32_16x16x32_bf16 v[60:63], v[132:135], v[202:205], v[60:63]
	v_mfma_f32_16x16x32_bf16 v[56:59], v[140:143], v[202:205], v[56:59]
	v_mfma_f32_16x16x32_bf16 v[44:47], v[132:135], v[232:235], v[44:47]
	v_mfma_f32_16x16x32_bf16 v[40:43], v[140:143], v[232:235], v[40:43]
	s_setprio 0
	s_setprio 1
	v_mfma_f32_16x16x32_bf16 v[84:87], v[144:147], v[182:185], 0
	v_mfma_f32_16x16x32_bf16 v[80:83], v[174:177], v[182:185], 0
	v_mfma_f32_16x16x32_bf16 v[68:71], v[144:147], v[190:193], 0
	v_mfma_f32_16x16x32_bf16 v[64:67], v[174:177], v[190:193], 0
	v_mfma_f32_16x16x32_bf16 v[52:55], v[144:147], v[198:201], 0
	v_mfma_f32_16x16x32_bf16 v[48:51], v[174:177], v[198:201], 0
	v_mfma_f32_16x16x32_bf16 v[36:39], v[144:147], v[206:209], 0
	v_mfma_f32_16x16x32_bf16 v[32:35], v[174:177], v[206:209], 0
	v_mfma_f32_16x16x32_bf16 v[84:87], v[148:151], v[186:189], v[84:87]
	v_mfma_f32_16x16x32_bf16 v[80:83], v[178:181], v[186:189], v[80:83]
	v_mfma_f32_16x16x32_bf16 v[68:71], v[148:151], v[194:197], v[68:71]
	v_mfma_f32_16x16x32_bf16 v[64:67], v[178:181], v[194:197], v[64:67]
	v_mfma_f32_16x16x32_bf16 v[52:55], v[148:151], v[202:205], v[52:55]
	v_mfma_f32_16x16x32_bf16 v[48:51], v[178:181], v[202:205], v[48:51]
	v_mfma_f32_16x16x32_bf16 v[36:39], v[148:151], v[232:235], v[36:39]
	v_mfma_f32_16x16x32_bf16 v[32:35], v[178:181], v[232:235], v[32:35]
	s_setprio 0
	s_barrier
	s_add_i32 s69, 0, 0x18000
	s_add_i32 s70, 0, 0x1c000
	v_add_u32_e32 v140, s69, v227
	v_add_u32_e32 v152, s70, v227
	ds_read_b128 v[128:131], v140
	ds_read_b128 v[132:135], v140 offset:1024
	ds_read_b128 v[136:139], v140 offset:2048
	ds_read_b128 v[140:143], v140 offset:3072
	ds_read_b128 v[144:147], v152
	ds_read_b128 v[148:151], v152 offset:1024
	ds_read_b128 v[174:177], v152 offset:2048
	ds_read_b128 v[178:181], v152 offset:3072
	s_add_u32 s46, s46, s26
	s_addc_u32 s47, s47, 0
	s_mov_b32 m0, s8
	v_lshl_add_u64 v[246:247], s[46:47], 0, v[158:159]
	ds_read_b128 v[182:185], v230 offset:32768
	ds_read_b128 v[186:189], v230 offset:33792
	ds_read_b128 v[190:193], v230 offset:34816
	ds_read_b128 v[194:197], v230 offset:35840
	ds_read_b128 v[198:201], v230 offset:36864
	ds_read_b128 v[202:205], v230 offset:37888
	ds_read_b128 v[206:209], v230 offset:38912
	ds_read_b128 v[232:235], v230 offset:39936
	global_load_lds_dwordx4 v[246:247], off
	v_lshl_add_u64 v[246:247], s[46:47], 0, v[162:163]
	s_mov_b32 m0, s9
	s_nop 0
	global_load_lds_dwordx4 v[246:247], off
	s_waitcnt vmcnt(8)
	s_waitcnt lgkmcnt(0)
	s_barrier
	s_setprio 1
	s_waitcnt lgkmcnt(0)
	v_mfma_f32_16x16x32_bf16 v[16:19], v[128:131], v[182:185], v[16:19]
	v_mfma_f32_16x16x32_bf16 v[28:31], v[136:139], v[182:185], v[28:31]
	v_mfma_f32_16x16x32_bf16 v[12:15], v[128:131], v[190:193], v[12:15]
	v_mfma_f32_16x16x32_bf16 v[8:11], v[136:139], v[190:193], v[8:11]
	v_mfma_f32_16x16x32_bf16 v[124:127], v[128:131], v[198:201], v[124:127]
	v_mfma_f32_16x16x32_bf16 v[120:123], v[136:139], v[198:201], v[120:123]
	v_mfma_f32_16x16x32_bf16 v[108:111], v[128:131], v[206:209], v[108:111]
	v_mfma_f32_16x16x32_bf16 v[104:107], v[136:139], v[206:209], v[104:107]
	v_mfma_f32_16x16x32_bf16 v[16:19], v[132:135], v[186:189], v[16:19]
	v_mfma_f32_16x16x32_bf16 v[28:31], v[140:143], v[186:189], v[28:31]
	v_mfma_f32_16x16x32_bf16 v[12:15], v[132:135], v[194:197], v[12:15]
	v_mfma_f32_16x16x32_bf16 v[8:11], v[140:143], v[194:197], v[8:11]
	v_mfma_f32_16x16x32_bf16 v[124:127], v[132:135], v[202:205], v[124:127]
	v_mfma_f32_16x16x32_bf16 v[120:123], v[140:143], v[202:205], v[120:123]
	v_mfma_f32_16x16x32_bf16 v[108:111], v[132:135], v[232:235], v[108:111]
	v_mfma_f32_16x16x32_bf16 v[104:107], v[140:143], v[232:235], v[104:107]
	s_setprio 0
	s_setprio 1
	v_mfma_f32_16x16x32_bf16 v[24:27], v[144:147], v[182:185], v[24:27]
	v_mfma_f32_16x16x32_bf16 v[20:23], v[174:177], v[182:185], v[20:23]
	v_mfma_f32_16x16x32_bf16 v[4:7], v[144:147], v[190:193], v[4:7]
	v_mfma_f32_16x16x32_bf16 v[0:3], v[174:177], v[190:193], v[0:3]
	v_mfma_f32_16x16x32_bf16 v[116:119], v[144:147], v[198:201], v[116:119]
	v_mfma_f32_16x16x32_bf16 v[112:115], v[174:177], v[198:201], v[112:115]
	v_mfma_f32_16x16x32_bf16 v[100:103], v[144:147], v[206:209], v[100:103]
	v_mfma_f32_16x16x32_bf16 v[96:99], v[174:177], v[206:209], v[96:99]
	v_mfma_f32_16x16x32_bf16 v[24:27], v[148:151], v[186:189], v[24:27]
	v_mfma_f32_16x16x32_bf16 v[20:23], v[178:181], v[186:189], v[20:23]
	v_mfma_f32_16x16x32_bf16 v[4:7], v[148:151], v[194:197], v[4:7]
	v_mfma_f32_16x16x32_bf16 v[0:3], v[178:181], v[194:197], v[0:3]
	v_mfma_f32_16x16x32_bf16 v[116:119], v[148:151], v[202:205], v[116:119]
	v_mfma_f32_16x16x32_bf16 v[112:115], v[178:181], v[202:205], v[112:115]
	v_mfma_f32_16x16x32_bf16 v[100:103], v[148:151], v[232:235], v[100:103]
	v_mfma_f32_16x16x32_bf16 v[96:99], v[178:181], v[232:235], v[96:99]
	s_setprio 0
	s_barrier
	s_add_i32 s46, s69, s3
	v_lshl_add_u64 v[210:211], v[210:211], 0, s[6:7]
	s_mov_b32 m0, s46
	ds_read_b128 v[182:185], v230 offset:49152
	ds_read_b128 v[186:189], v230 offset:50176
	ds_read_b128 v[190:193], v230 offset:51200
	ds_read_b128 v[194:197], v230 offset:52224
	ds_read_b128 v[198:201], v230 offset:53248
	ds_read_b128 v[202:205], v230 offset:54272
	ds_read_b128 v[206:209], v230 offset:55296
	ds_read_b128 v[232:235], v230 offset:56320
	global_load_lds_dwordx4 v[210:211], off
	v_lshl_add_u64 v[210:211], v[236:237], 0, s[6:7]
	s_add_i32 m0, s46, 0x2000
	s_add_i32 s46, s70, s3
	global_load_lds_dwordx4 v[210:211], off
	v_lshl_add_u64 v[210:211], v[238:239], 0, s[6:7]
	s_mov_b32 m0, s46
	s_nop 0
	global_load_lds_dwordx4 v[210:211], off
	v_lshl_add_u64 v[210:211], v[240:241], 0, s[6:7]
	s_add_i32 m0, s46, 0x2000
	s_nop 0
	global_load_lds_dwordx4 v[210:211], off
	v_lshl_add_u64 v[210:211], v[242:243], 0, s[6:7]
	s_mov_b32 m0, s30
	s_nop 0
	global_load_lds_dwordx4 v[210:211], off
	v_lshl_add_u64 v[210:211], v[244:245], 0, s[6:7]
	s_mov_b32 m0, s31
	s_nop 0
	global_load_lds_dwordx4 v[210:211], off
	s_waitcnt vmcnt(8)
	s_waitcnt lgkmcnt(0)
	s_barrier
	s_setprio 1
	s_waitcnt lgkmcnt(0)
	v_mfma_f32_16x16x32_bf16 v[92:95], v[128:131], v[182:185], v[92:95]
	v_mfma_f32_16x16x32_bf16 v[88:91], v[136:139], v[182:185], v[88:91]
	v_mfma_f32_16x16x32_bf16 v[76:79], v[128:131], v[190:193], v[76:79]
	v_mfma_f32_16x16x32_bf16 v[72:75], v[136:139], v[190:193], v[72:75]
	v_mfma_f32_16x16x32_bf16 v[60:63], v[128:131], v[198:201], v[60:63]
	v_mfma_f32_16x16x32_bf16 v[56:59], v[136:139], v[198:201], v[56:59]
	v_mfma_f32_16x16x32_bf16 v[44:47], v[128:131], v[206:209], v[44:47]
	v_mfma_f32_16x16x32_bf16 v[40:43], v[136:139], v[206:209], v[40:43]
	v_mfma_f32_16x16x32_bf16 v[92:95], v[132:135], v[186:189], v[92:95]
	v_mfma_f32_16x16x32_bf16 v[88:91], v[140:143], v[186:189], v[88:91]
	v_mfma_f32_16x16x32_bf16 v[76:79], v[132:135], v[194:197], v[76:79]
	v_mfma_f32_16x16x32_bf16 v[72:75], v[140:143], v[194:197], v[72:75]
	v_mfma_f32_16x16x32_bf16 v[60:63], v[132:135], v[202:205], v[60:63]
	v_mfma_f32_16x16x32_bf16 v[56:59], v[140:143], v[202:205], v[56:59]
	v_mfma_f32_16x16x32_bf16 v[44:47], v[132:135], v[232:235], v[44:47]
	v_mfma_f32_16x16x32_bf16 v[40:43], v[140:143], v[232:235], v[40:43]
	s_setprio 0
	s_setprio 1
	v_mfma_f32_16x16x32_bf16 v[84:87], v[144:147], v[182:185], v[84:87]
	v_mfma_f32_16x16x32_bf16 v[80:83], v[174:177], v[182:185], v[80:83]
	v_mfma_f32_16x16x32_bf16 v[68:71], v[144:147], v[190:193], v[68:71]
	v_mfma_f32_16x16x32_bf16 v[64:67], v[174:177], v[190:193], v[64:67]
	v_mfma_f32_16x16x32_bf16 v[52:55], v[144:147], v[198:201], v[52:55]
	v_mfma_f32_16x16x32_bf16 v[48:51], v[174:177], v[198:201], v[48:51]
	v_mfma_f32_16x16x32_bf16 v[36:39], v[144:147], v[206:209], v[36:39]
	v_mfma_f32_16x16x32_bf16 v[32:35], v[174:177], v[206:209], v[32:35]
	v_mfma_f32_16x16x32_bf16 v[84:87], v[148:151], v[186:189], v[84:87]
	v_mfma_f32_16x16x32_bf16 v[80:83], v[178:181], v[186:189], v[80:83]
	v_mfma_f32_16x16x32_bf16 v[68:71], v[148:151], v[194:197], v[68:71]
	v_mfma_f32_16x16x32_bf16 v[64:67], v[178:181], v[194:197], v[64:67]
	v_mfma_f32_16x16x32_bf16 v[52:55], v[148:151], v[202:205], v[52:55]
	v_mfma_f32_16x16x32_bf16 v[48:51], v[178:181], v[202:205], v[48:51]
	v_mfma_f32_16x16x32_bf16 v[36:39], v[148:151], v[232:235], v[36:39]
	v_mfma_f32_16x16x32_bf16 v[32:35], v[178:181], v[232:235], v[32:35]
	s_setprio 0
	s_barrier
	s_add_u32 s44, s44, 0x100
	s_addc_u32 s45, s45, 0
	s_add_u32 s23, s23, 0x100
	s_addc_u32 s48, s48, 0
	s_cmp_ge_u32 s49, s88
	s_mov_b32 s46, s49
	s_cbranch_scc1 .LBB0_249

.Lk_zero_skip:
	v_mov_b32_e32 v19, 0
	v_mov_b32_e32 v18, v19
	v_mov_b32_e32 v17, v19
	v_mov_b32_e32 v16, v19
	v_mov_b32_e32 v31, v19
	v_mov_b32_e32 v30, v19
	v_mov_b32_e32 v29, v19
	v_mov_b32_e32 v28, v19
	v_mov_b32_e32 v15, v19
	v_mov_b32_e32 v14, v19
	v_mov_b32_e32 v13, v19
	v_mov_b32_e32 v12, v19
	v_mov_b32_e32 v11, v19
	v_mov_b32_e32 v10, v19
	v_mov_b32_e32 v9, v19
	v_mov_b32_e32 v8, v19
	v_mov_b32_e32 v127, v19
	v_mov_b32_e32 v126, v19
	v_mov_b32_e32 v125, v19
	v_mov_b32_e32 v124, v19
	v_mov_b32_e32 v123, v19
	v_mov_b32_e32 v122, v19
	v_mov_b32_e32 v121, v19
	v_mov_b32_e32 v120, v19
	v_mov_b32_e32 v111, v19
	v_mov_b32_e32 v110, v19
	v_mov_b32_e32 v109, v19
	v_mov_b32_e32 v108, v19
	v_mov_b32_e32 v107, v19
	v_mov_b32_e32 v106, v19
	v_mov_b32_e32 v105, v19
	v_mov_b32_e32 v104, v19
	v_mov_b32_e32 v27, v19
	v_mov_b32_e32 v26, v19
	v_mov_b32_e32 v25, v19
	v_mov_b32_e32 v24, v19
	v_mov_b32_e32 v23, v19
	v_mov_b32_e32 v22, v19
	v_mov_b32_e32 v21, v19
	v_mov_b32_e32 v20, v19
	v_mov_b32_e32 v7, v19
	v_mov_b32_e32 v6, v19
	v_mov_b32_e32 v5, v19
	v_mov_b32_e32 v4, v19
	v_mov_b32_e32 v3, v19
	v_mov_b32_e32 v2, v19
	v_mov_b32_e32 v1, v19
	v_mov_b32_e32 v0, v19
	v_mov_b32_e32 v119, v19
	v_mov_b32_e32 v118, v19
	v_mov_b32_e32 v117, v19
	v_mov_b32_e32 v116, v19
	v_mov_b32_e32 v115, v19
	v_mov_b32_e32 v114, v19
	v_mov_b32_e32 v113, v19
	v_mov_b32_e32 v112, v19
	v_mov_b32_e32 v103, v19
	v_mov_b32_e32 v102, v19
	v_mov_b32_e32 v101, v19
	v_mov_b32_e32 v100, v19
	v_mov_b32_e32 v99, v19
	v_mov_b32_e32 v98, v19
	v_mov_b32_e32 v97, v19
	v_mov_b32_e32 v96, v19
	v_mov_b32_e32 v95, v19
	v_mov_b32_e32 v94, v19
	v_mov_b32_e32 v93, v19
	v_mov_b32_e32 v92, v19
	v_mov_b32_e32 v91, v19
	v_mov_b32_e32 v90, v19
	v_mov_b32_e32 v89, v19
	v_mov_b32_e32 v88, v19
	v_mov_b32_e32 v79, v19
	v_mov_b32_e32 v78, v19
	v_mov_b32_e32 v77, v19
	v_mov_b32_e32 v76, v19
	v_mov_b32_e32 v75, v19
	v_mov_b32_e32 v74, v19
	v_mov_b32_e32 v73, v19
	v_mov_b32_e32 v72, v19
	v_mov_b32_e32 v63, v19
	v_mov_b32_e32 v62, v19
	v_mov_b32_e32 v61, v19
	v_mov_b32_e32 v60, v19
	v_mov_b32_e32 v59, v19
	v_mov_b32_e32 v58, v19
	v_mov_b32_e32 v57, v19
	v_mov_b32_e32 v56, v19
	v_mov_b32_e32 v47, v19
	v_mov_b32_e32 v46, v19
	v_mov_b32_e32 v45, v19
	v_mov_b32_e32 v44, v19
	v_mov_b32_e32 v43, v19
	v_mov_b32_e32 v42, v19
	v_mov_b32_e32 v41, v19
	v_mov_b32_e32 v40, v19
	v_mov_b32_e32 v87, v19
	v_mov_b32_e32 v86, v19
	v_mov_b32_e32 v85, v19
	v_mov_b32_e32 v84, v19
	v_mov_b32_e32 v83, v19
	v_mov_b32_e32 v82, v19
	v_mov_b32_e32 v81, v19
	v_mov_b32_e32 v80, v19
	v_mov_b32_e32 v71, v19
	v_mov_b32_e32 v70, v19
	v_mov_b32_e32 v69, v19
	v_mov_b32_e32 v68, v19
	v_mov_b32_e32 v67, v19
	v_mov_b32_e32 v66, v19
	v_mov_b32_e32 v65, v19
	v_mov_b32_e32 v64, v19
	v_mov_b32_e32 v55, v19
	v_mov_b32_e32 v54, v19
	v_mov_b32_e32 v53, v19
	v_mov_b32_e32 v52, v19
	v_mov_b32_e32 v51, v19
	v_mov_b32_e32 v50, v19
	v_mov_b32_e32 v49, v19
	v_mov_b32_e32 v48, v19
	v_mov_b32_e32 v39, v19
	v_mov_b32_e32 v38, v19
	v_mov_b32_e32 v37, v19
	v_mov_b32_e32 v36, v19
	v_mov_b32_e32 v35, v19
	v_mov_b32_e32 v34, v19
	v_mov_b32_e32 v33, v19
	v_mov_b32_e32 v32, v19
	s_branch .LBB0_249
